# v56 + scan step A2: 23 packed-f32 ops (v_pk_mul_f32 / v_pk_fma_f32) split into scalar v_mul_f32 / v_fma_f32 pairs (tests whether packed f32 issue is slow here)
# baseline (speedup 1.0000x reference)
.LBB0_565:
	v_cndmask_b32_e64 v8, 0, 1, s[34:35]
	v_cmp_ne_u32_e64 s[24:25], 1, v8
	s_andn2_b64 vcc, exec, s[34:35]
	s_cbranch_vccnz .LBB0_573
	ds_read_b128 v[20:23], v226 offset:1536
	ds_read_b128 v[24:27], v226 offset:1792
	ds_read_b128 v[28:31], v226 offset:1600
	ds_read_b128 v[32:35], v226 offset:1856
	ds_read_b64 v[36:37], v115 offset:56320
	ds_read_b64 v[38:39], v116 offset:56320
	ds_read_b64 v[40:41], v227
	ds_read_b64 v[42:43], v228
	ds_read2_b64 v[82:85], v229 offset1:4
	ds_read2_b64 v[158:161], v230 offset1:4
	s_waitcnt lgkmcnt(1)
	v_mfma_f32_16x16x32_f16 v[20:23], v[82:85], v[36:39], v[20:23]
	ds_read2_b64 v[82:85], v231 offset1:4
	s_waitcnt lgkmcnt(1)
	v_mfma_f32_16x16x32_f16 v[24:27], v[158:161], v[40:43], v[24:27]
	ds_read2_b64 v[158:161], v232 offset1:4
	s_add_i32 s38, 0, 0x14800
	s_waitcnt lgkmcnt(1)
	v_mfma_f32_16x16x32_f16 v[28:31], v[82:85], v[36:39], v[28:31]
	ds_read_b64 v[36:37], v119 offset:56320
	ds_read_b64 v[38:39], v120 offset:56320
	s_waitcnt lgkmcnt(2)
	v_mfma_f32_16x16x32_f16 v[32:35], v[158:161], v[40:43], v[32:35]
	ds_read_b64 v[40:41], v233
	ds_read_b64 v[42:43], v234
	ds_read2_b64 v[82:85], v235 offset1:4
	ds_read2_b64 v[158:161], v236 offset1:4
	s_waitcnt lgkmcnt(1)
	v_mfma_f32_16x16x32_f16 v[82:85], v[82:85], v[36:39], v[20:23]
	s_nop 2
	ds_read2_b64 v[20:23], v237 offset1:4
	ds_read2_b64 v[162:165], v238 offset1:4
	s_waitcnt lgkmcnt(2)
	v_mfma_f32_16x16x32_f16 v[158:161], v[158:161], v[40:43], v[24:27]
	ds_read2st64_b32 v[8:9], v239 offset1:1
	s_waitcnt lgkmcnt(2)
	v_mfma_f32_16x16x32_f16 v[24:27], v[20:23], v[36:39], v[28:31]
	v_exp_f32_e32 v36, v82
	s_nop 3
	v_exp_f32_e32 v37, v158
	s_waitcnt lgkmcnt(0)
	v_add_f32_e32 v8, v8, v9
	v_mfma_f32_16x16x32_f16 v[20:23], v[162:165], v[40:43], v[32:35]
	v_fmamk_f32 v36, v36, 0xbf92477c, v147
	v_rcp_f32_e32 v36, v36
	v_add_f32_e32 v37, 1.0, v37
	v_rcp_f32_e32 v86, v37
	s_nop 0
	v_add_f32_dpp v37, v36, v36 row_shr:1 row_mask:0xf bank_mask:0xf bound_ctrl:1
	v_lshlrev_b32_e32 v9, 2, v240
	v_or_b32_e32 v157, 60, v9
	v_add_f32_dpp v37, v37, v37 row_shr:2 row_mask:0xf bank_mask:0xf bound_ctrl:1
	v_add_u32_e32 v32, s38, v123
	ds_read_b128 v[28:31], v32 offset:1280
	ds_read_b128 v[32:35], v32 offset:4864
	v_add_f32_dpp v37, v37, v37 row_shr:4 row_mask:0xf bank_mask:0xf bound_ctrl:1
	s_nop 1
	v_add_f32_dpp v82, v37, v37 row_shr:8 row_mask:0xf bank_mask:0xf bound_ctrl:1
	v_sub_f32_e32 v162, v82, v36
	v_exp_f32_e32 v36, v83
	v_exp_f32_e32 v37, v159
	ds_bpermute_b32 v40, v9, v82 offset:28
	v_max_f32_e32 v8, 0x179abe15, v8
	v_fmamk_f32 v36, v36, 0xbf92477c, v147
	v_rcp_f32_e32 v36, v36
	v_add_f32_e32 v37, 1.0, v37
	v_rcp_f32_e32 v87, v37
	v_rsq_f32_e32 v8, v8
	v_add_f32_dpp v37, v36, v36 row_shr:1 row_mask:0xf bank_mask:0xf bound_ctrl:1
	s_waitcnt lgkmcnt(1)
	v_fma_f32 v28, v86, v28, v32
	v_fma_f32 v29, v87, v29, v33
	v_add_f32_dpp v37, v37, v37 row_shr:2 row_mask:0xf bank_mask:0xf bound_ctrl:1
	s_nop 1
	v_add_f32_dpp v37, v37, v37 row_shr:4 row_mask:0xf bank_mask:0xf bound_ctrl:1
	s_nop 1
	v_add_f32_dpp v83, v37, v37 row_shr:8 row_mask:0xf bank_mask:0xf bound_ctrl:1
	v_sub_f32_e32 v163, v83, v36
	v_exp_f32_e32 v36, v84
	v_exp_f32_e32 v37, v160
	ds_bpermute_b32 v41, v9, v83 offset:28
	s_waitcnt lgkmcnt(1)
	v_sub_f32_e32 v84, v162, v40
	v_fmamk_f32 v36, v36, 0xbf92477c, v147
	v_rcp_f32_e32 v36, v36
	v_add_f32_e32 v37, 1.0, v37
	v_rcp_f32_e32 v158, v37
	v_exp_f32_e32 v160, v84
	v_add_f32_dpp v37, v36, v36 row_shr:1 row_mask:0xf bank_mask:0xf bound_ctrl:1
	s_nop 1
	v_add_f32_dpp v37, v37, v37 row_shr:2 row_mask:0xf bank_mask:0xf bound_ctrl:1
	s_nop 1
	v_add_f32_dpp v37, v37, v37 row_shr:4 row_mask:0xf bank_mask:0xf bound_ctrl:1
	s_nop 1
	v_add_f32_dpp v166, v37, v37 row_shr:8 row_mask:0xf bank_mask:0xf bound_ctrl:1
	v_sub_f32_e32 v167, v166, v36
	v_exp_f32_e32 v36, v85
	v_exp_f32_e32 v37, v161
	ds_bpermute_b32 v42, v9, v166 offset:28
	ds_bpermute_b32 v38, v157, v166
	v_fmamk_f32 v36, v36, 0xbf92477c, v147
	v_rcp_f32_e32 v36, v36
	v_add_f32_e32 v37, 1.0, v37
	v_rcp_f32_e32 v159, v37
	s_waitcnt lgkmcnt(1)
	v_sub_f32_e32 v32, v167, v42
	v_add_f32_dpp v37, v36, v36 row_shr:1 row_mask:0xf bank_mask:0xf bound_ctrl:1
	v_sub_f32_e32 v33, v166, v42
	v_exp_f32_e32 v166, v33
	v_add_f32_dpp v37, v37, v37 row_shr:2 row_mask:0xf bank_mask:0xf bound_ctrl:1
	v_fma_f32 v30, v158, v30, v34
	v_fma_f32 v31, v159, v31, v35
	v_exp_f32_e32 v32, v32
	v_add_f32_dpp v37, v37, v37 row_shr:4 row_mask:0xf bank_mask:0xf bound_ctrl:1
	v_rcp_f32_e32 v168, v166
	s_nop 0
	v_add_f32_dpp v169, v37, v37 row_shr:8 row_mask:0xf bank_mask:0xf bound_ctrl:1
	v_sub_f32_e32 v170, v169, v36
	ds_bpermute_b32 v36, v157, v82
	v_sub_f32_e32 v82, v82, v40
	v_exp_f32_e32 v84, v82
	v_sub_f32_e32 v82, v163, v41
	v_exp_f32_e32 v161, v82
	v_sub_f32_e32 v82, v83, v41
	ds_bpermute_b32 v43, v9, v169 offset:28
	v_exp_f32_e32 v85, v82
	ds_bpermute_b32 v37, v157, v83
	v_rcp_f32_e32 v162, v84
	v_rcp_f32_e32 v163, v85
	v_fma_mix_f32 v164, v74, v84, 0 op_sel_hi:[1,0,0]
	v_fma_mix_f32 v165, v74, v85, 0 op_sel:[1,0,0] op_sel_hi:[1,0,0]
	s_waitcnt lgkmcnt(1)
	v_sub_f32_e32 v167, v169, v43
	v_exp_f32_e32 v167, v167
	v_fma_mix_f32 v82, v66, v28, 0 op_sel_hi:[1,0,0]
	v_fma_mix_f32 v83, v66, v29, 0 op_sel:[1,0,0] op_sel_hi:[1,0,0]
	v_sub_f32_e32 v33, v170, v43
	v_fma_mix_f32 v84, v67, v30, 0 op_sel_hi:[1,0,0]
	v_fma_mix_f32 v85, v67, v31, 0 op_sel:[1,0,0] op_sel_hi:[1,0,0]
	v_exp_f32_e32 v33, v33
	ds_bpermute_b32 v39, v157, v169
	v_rcp_f32_e32 v169, v167
	v_fma_mix_f32 v28, v68, v8, 0 op_sel_hi:[1,0,0]
	v_fma_mix_f32 v29, v68, v8, 0 op_sel:[1,0,0] op_sel_hi:[1,0,0]
	v_fma_mix_f32 v30, v69, v8, 0 op_sel_hi:[1,0,0]
	v_fma_mix_f32 v31, v69, v8, 0 op_sel:[1,0,0] op_sel_hi:[1,0,0]
	v_mul_f32_e32 v34, v28, v160
	v_mul_f32_e32 v35, v29, v161
	v_mul_f32_e32 v32, v30, v32
	v_mul_f32_e32 v33, v31, v33
	v_mul_f32_e32 v28, v86, v28
	v_mul_f32_e32 v29, v87, v29
	v_mul_f32_e32 v30, v158, v30
	v_mul_f32_e32 v31, v159, v31
	v_fma_mix_f32 v166, v75, v166, 0 op_sel_hi:[1,0,0]
	v_fma_mix_f32 v167, v75, v167, 0 op_sel:[1,0,0] op_sel_hi:[1,0,0]
	v_mul_f32_e32 v28, v28, v162
	v_mul_f32_e32 v29, v29, v163
	v_mul_f32_e32 v30, v30, v168
	v_mul_f32_e32 v31, v31, v169
	v_mul_f32_e32 v86, v82, v162
	v_mul_f32_e32 v87, v83, v163
	v_mul_f32_e32 v158, v84, v168
	v_mul_f32_e32 v159, v85, v169
	v_cvt_pk_f16_f32 v33, v32, v33
	v_cvt_pk_f16_f32 v32, v34, v35
	ds_write_b64 v214, v[32:33]
	v_cvt_pk_f16_f32 v33, v166, v167
	v_cvt_pk_f16_f32 v32, v164, v165
	v_cvt_pk_f16_f32 v31, v30, v31
	v_cvt_pk_f16_f32 v30, v28, v29
	v_cvt_pk_f16_f32 v29, v158, v159
	v_cvt_pk_f16_f32 v28, v86, v87
	ds_write_b64 v214, v[32:33] offset:2304
	ds_write_b64 v214, v[30:31] offset:4608
	ds_write_b64 v214, v[28:29] offset:6912
	s_waitcnt lgkmcnt(4)
	s_and_saveexec_b64 s[34:35], s[4:5]
	s_cbranch_execz .LBB0_568
	v_add_u32_e32 v28, s71, v123
	ds_write_b128 v28, v[40:43] offset:13568
	s_waitcnt lgkmcnt(0)
	ds_write_b128 v28, v[36:39] offset:13824
.LBB0_568:
	s_or_b64 exec, exec, s[34:35]
	v_exp_f32_e32 v24, v24
	v_exp_f32_e32 v20, v20
	v_exp_f32_e32 v21, v21
	v_or_b32_e32 v40, 28, v9
	v_fmamk_f32 v24, v24, 0xbf92477c, v147
	v_rcp_f32_e32 v24, v24
	v_add_f32_e32 v20, 1.0, v20
	v_rcp_f32_e32 v36, v20
	v_add_f32_e32 v21, 1.0, v21
	v_add_f32_dpp v20, v24, v24 row_shr:1 row_mask:0xf bank_mask:0xf bound_ctrl:1
	v_rcp_f32_e32 v37, v21
	v_add_u32_e32 v32, s38, v124
	v_add_f32_dpp v20, v20, v20 row_shr:2 row_mask:0xf bank_mask:0xf bound_ctrl:1
	ds_read_b128 v[28:31], v32 offset:1280
	ds_read_b128 v[32:35], v32 offset:4864
	v_add_f32_dpp v20, v20, v20 row_shr:4 row_mask:0xf bank_mask:0xf bound_ctrl:1
	v_cvt_f32_f16_sdwa v161, v70 dst_sel:DWORD dst_unused:UNUSED_PAD src0_sel:WORD_1
	v_cvt_f32_f16_e32 v160, v70
	v_add_f32_dpp v41, v20, v20 row_shr:8 row_mask:0xf bank_mask:0xf bound_ctrl:1
	v_exp_f32_e32 v20, v25
	v_sub_f32_e32 v42, v41, v24
	ds_bpermute_b32 v24, v40, v41
	s_waitcnt lgkmcnt(1)
	v_fma_f32 v28, v36, v28, v32
	v_fma_f32 v29, v37, v29, v33
	v_fmamk_f32 v20, v20, 0xbf92477c, v147
	v_rcp_f32_e32 v20, v20
	v_fma_f32 v28, v160, v28, 0
	v_fma_f32 v29, v161, v29, 0
	v_cvt_f32_f16_sdwa v159, v78 dst_sel:DWORD dst_unused:UNUSED_PAD src0_sel:WORD_1
	v_cvt_f32_f16_e32 v158, v78
	v_add_f32_dpp v21, v20, v20 row_shr:1 row_mask:0xf bank_mask:0xf bound_ctrl:1
	s_nop 1
	v_add_f32_dpp v21, v21, v21 row_shr:2 row_mask:0xf bank_mask:0xf bound_ctrl:1
	v_mov_b32_e32 v9, v8
	s_nop 0
	v_add_f32_dpp v21, v21, v21 row_shr:4 row_mask:0xf bank_mask:0xf bound_ctrl:1
	v_fma_mix_f32 v32, v72, v8, 0 op_sel_hi:[1,0,0]
	v_fma_mix_f32 v33, v72, v9, 0 op_sel:[1,0,0] op_sel_hi:[1,0,0]
	v_add_f32_dpp v43, v21, v21 row_shr:8 row_mask:0xf bank_mask:0xf bound_ctrl:1
	v_sub_f32_e32 v87, v43, v20
	v_exp_f32_e32 v20, v26
	v_exp_f32_e32 v21, v22
	ds_bpermute_b32 v25, v40, v43
	v_fmamk_f32 v20, v20, 0xbf92477c, v147
	v_rcp_f32_e32 v20, v20
	v_add_f32_e32 v21, 1.0, v21
	v_rcp_f32_e32 v38, v21
	s_nop 0
	v_add_f32_dpp v21, v20, v20 row_shr:1 row_mask:0xf bank_mask:0xf bound_ctrl:1
	s_nop 1
	v_add_f32_dpp v21, v21, v21 row_shr:2 row_mask:0xf bank_mask:0xf bound_ctrl:1
	s_nop 1
	v_add_f32_dpp v21, v21, v21 row_shr:4 row_mask:0xf bank_mask:0xf bound_ctrl:1
	s_nop 1
	v_add_f32_dpp v162, v21, v21 row_shr:8 row_mask:0xf bank_mask:0xf bound_ctrl:1
	v_sub_f32_e32 v163, v162, v20
	v_exp_f32_e32 v20, v27
	v_exp_f32_e32 v21, v23
	ds_bpermute_b32 v26, v40, v162
	ds_bpermute_b32 v22, v157, v162
	v_fmamk_f32 v20, v20, 0xbf92477c, v147
	v_rcp_f32_e32 v20, v20
	v_add_f32_e32 v21, 1.0, v21
	v_rcp_f32_e32 v39, v21
	s_nop 0
	v_add_f32_dpp v21, v20, v20 row_shr:1 row_mask:0xf bank_mask:0xf bound_ctrl:1
	v_fma_f32 v30, v38, v30, v34
	v_fma_f32 v31, v39, v31, v35
	v_add_f32_dpp v21, v21, v21 row_shr:2 row_mask:0xf bank_mask:0xf bound_ctrl:1
	v_cvt_f32_f16_sdwa v35, v73 dst_sel:DWORD dst_unused:UNUSED_PAD src0_sel:WORD_1
	v_cvt_f32_f16_e32 v34, v73
	v_add_f32_dpp v21, v21, v21 row_shr:4 row_mask:0xf bank_mask:0xf bound_ctrl:1
	v_fma_f32 v8, v34, v8, 0
	v_fma_f32 v9, v35, v9, 0
	v_add_f32_dpp v165, v21, v21 row_shr:8 row_mask:0xf bank_mask:0xf bound_ctrl:1
	ds_bpermute_b32 v27, v40, v165
	v_sub_f32_e32 v166, v165, v20
	ds_bpermute_b32 v20, v157, v41
	ds_bpermute_b32 v21, v157, v43
	ds_bpermute_b32 v23, v157, v165
	s_waitcnt lgkmcnt(5)
	v_sub_f32_e32 v157, v163, v26
	v_exp_f32_e32 v160, v157
	v_sub_f32_e32 v157, v162, v26
	v_exp_f32_e32 v162, v157
	s_waitcnt lgkmcnt(3)
	v_sub_f32_e32 v157, v166, v27
	v_sub_f32_e32 v41, v41, v24
	v_sub_f32_e32 v43, v43, v25
	v_exp_f32_e32 v161, v157
	v_sub_f32_e32 v157, v165, v27
	v_sub_f32_e32 v40, v42, v24
	v_exp_f32_e32 v42, v41
	v_exp_f32_e32 v43, v43
	v_exp_f32_e32 v163, v157
	v_sub_f32_e32 v41, v87, v25
	v_exp_f32_e32 v40, v40
	v_exp_f32_e32 v41, v41
	v_rcp_f32_e32 v86, v42
	v_rcp_f32_e32 v87, v43
	v_rcp_f32_e32 v164, v162
	v_rcp_f32_e32 v165, v163
	v_fma_f32 v42, v158, v42, 0
	v_fma_f32 v43, v159, v43, 0
	v_fma_mix_f32 v158, v79, v162, 0 op_sel_hi:[1,0,0]
	v_fma_mix_f32 v159, v79, v163, 0 op_sel:[1,0,0] op_sel_hi:[1,0,0]
	v_mul_f32_e32 v34, v32, v40
	v_mul_f32_e32 v35, v33, v41
	v_mul_f32_e32 v40, v8, v160
	v_mul_f32_e32 v41, v9, v161
	v_mul_f32_e32 v32, v36, v32
	v_mul_f32_e32 v33, v37, v33
	v_mul_f32_e32 v8, v38, v8
	v_mul_f32_e32 v9, v39, v9
	v_fma_mix_f32 v30, v71, v30, 0 op_sel_hi:[1,0,0]
	v_fma_mix_f32 v31, v71, v31, 0 op_sel:[1,0,0] op_sel_hi:[1,0,0]
	v_mul_f32_e32 v32, v32, v86
	v_mul_f32_e32 v33, v33, v87
	v_mul_f32_e32 v8, v8, v164
	v_mul_f32_e32 v9, v9, v165
	v_mul_f32_e32 v36, v28, v86
	v_mul_f32_e32 v37, v29, v87
	v_mul_f32_e32 v38, v30, v164
	v_mul_f32_e32 v39, v31, v165
	v_add_u32_e32 v86, s71, v114
	v_cvt_pk_f16_f32 v9, v8, v9
	v_cvt_pk_f16_f32 v8, v32, v33
	v_cvt_pk_f16_f32 v41, v40, v41
	v_cvt_pk_f16_f32 v40, v34, v35
	v_cvt_pk_f16_f32 v35, v158, v159
	v_cvt_pk_f16_f32 v34, v42, v43
	ds_write_b64 v86, v[8:9] offset:4608
	v_cvt_pk_f16_f32 v9, v38, v39
	v_cvt_pk_f16_f32 v8, v36, v37
	ds_write_b64 v86, v[40:41]
	ds_write_b64 v86, v[34:35] offset:2304
	ds_write_b64 v86, v[8:9] offset:6912
	s_waitcnt lgkmcnt(4)
	s_and_saveexec_b64 s[34:35], s[4:5]
	s_cbranch_execz .LBB0_570
	v_add_u32_e32 v8, s71, v124
	ds_write_b128 v8, v[24:27] offset:13568
	ds_write_b128 v8, v[20:23] offset:13824
